# v36 + P4 weight conversion: odd waves enter the load/transposed-store loop ~2.7 us later so one half's loads overlap the other half's stores
# baseline (speedup 1.0000x reference)
; #define LAS __attribute__((address_space(3)))
; template <class Resolve>
; DI void p0_convert(const Resolve R, int first, int stride, int total, LAS float* scr, int lane) {
;     for (int it = first; it < total; it += 2 * stride) {
;         const bool two = it + stride < total;
;         const TItem t0 = R(it), t1 = R(two ? it + stride : it);
; __global__ void __launch_bounds__(512, 2) fwd_kernel(Args a) {
;     ...
;         {
;             LAS float* scr = (LAS float*)(lds + wid * 17408);
;             p0_convert(ResRest{w_out, w_up, w_dn, WOUT, WUP, WDN, ln2_g}, bx * 8 + wid, G * 8, NP0_REST, scr, lane);
;         }
.LBB0_437:
	s_lshl_b32 s0, s92, 3
	v_readlane_b32 s1, v254, 6
	s_bitcmp0_b32 s1, 0
	s_cbranch_scc1 .Lmy_cvskew
	s_sleep 100
.Lmy_cvskew:
	s_add_i32 s20, s1, s0
	v_readlane_b32 s30, v254, 41
	s_cmpk_gt_i32 s20, 0x23ff
	v_readlane_b32 s31, v254, 42
	s_cbranch_scc1 .LBB0_457
	v_readlane_b32 s0, v254, 6
	s_mulk_i32 s0, 0x4400
	v_lshlrev_b32_e32 v0, 2, v253
	s_add_i32 s0, s0, 0
	v_lshrrev_b32_e32 v72, 3, v152
	v_and_b32_e32 v0, 28, v0
	v_and_b32_e32 v1, 7, v253
	v_mov_b32_e32 v65, 0
	v_lshl_add_u32 v3, v1, 4, s0
	v_mul_u32_u24_e32 v4, 0x84, v72
	v_lshlrev_b32_e32 v2, 3, v1
	v_mul_u32_u24_e32 v1, 0x420, v1
	v_lshlrev_b32_e32 v5, 2, v72
	v_lshlrev_b32_e32 v66, 2, v0
	s_lshl_b32 s21, s64, 3
	v_or_b32_e32 v73, 8, v72
	v_or_b32_e32 v74, 16, v72
	v_or_b32_e32 v75, 24, v72
	v_add3_u32 v76, s0, v1, v5
	s_lshl_b32 s22, s64, 4
	v_mov_b32_e32 v68, v66
	v_mov_b32_e32 v69, v65
	v_lshlrev_b32_e32 v64, 1, v2
	v_add_u32_e32 v77, v3, v4
	s_branch .LBB0_440
